# adds one static s_setprio 1 for waves 4-7 inside the diff-attention tile loop (on top of SB wave stagger and batched F r-table loads)
# speedup vs baseline: 1.0091x; 1.0008x over previous
.LBB0_261:
	v_mov_b32_e32 v16, v208
	s_ashr_i32 s0, s8, 5
	s_sub_i32 s8, 63, s0
	v_readfirstlane_b32 s1, v16
	s_ashr_i32 s14, s1, 7
	s_ashr_i32 s6, s1, 6
	s_lshl_b32 s1, s8, 7
	s_lshl_b32 s7, s14, 5
	s_ashr_i32 s12, s9, 4
	v_and_b32_e32 v17, 31, v16
	s_add_i32 s9, s7, s1
	v_or_b32_e32 v2, s9, v17
	s_and_b32 s15, s6, 1
	s_ashr_i32 s13, s12, 31
	v_ashrrev_i32_e32 v3, 31, v2
	s_lshl_b64 s[18:19], s[12:13], 24
	v_lshlrev_b64 v[2:3], 11, v[2:3]
	s_lshl_b32 s9, s15, 7
	s_lshl_b32 s11, s10, 8
	v_lshl_add_u64 v[200:201], v[2:3], 0, s[18:19]
	s_or_b32 s84, s9, s11
	s_lshl_b32 s50, s10, 7
	s_lshl_b64 s[20:21], s[12:13], 25
	s_lshr_b32 s18, s1, 6
	s_add_u32 s1, s35, s20
	v_bfe_u32 v214, v16, 5, 1
	v_lshl_add_u64 v[2:3], v[200:201], 1, s[4:5]
	s_addc_u32 s13, s37, s21
	v_lshl_add_u64 v[2:3], v[2:3], 0, s[84:85]
	v_lshlrev_b32_e32 v0, 4, v214
	s_add_u32 s20, s1, s11
	v_lshl_add_u64 v[2:3], v[2:3], 0, v[0:1]
	v_bfe_u32 v0, v16, 3, 3
	s_addc_u32 s21, s13, 0
	s_lshl_b32 s12, s12, 7
	v_lshl_or_b32 v0, s6, 3, v0
	s_ashr_i32 s13, s12, 31
	global_load_dwordx4 v[114:117], v[2:3], off
	global_load_dwordx4 v[118:121], v[2:3], off offset:32
	global_load_dwordx4 v[122:125], v[2:3], off offset:64
	global_load_dwordx4 v[126:129], v[2:3], off offset:96
	v_lshrrev_b32_e32 v2, 1, v0
	s_lshl_b64 s[12:13], s[12:13], 18
	v_xor_b32_e32 v2, v2, v16
	s_add_u32 s1, s36, s12
	v_readlane_b32 s11, v252, 50
	v_lshlrev_b32_e32 v2, 3, v2
	s_addc_u32 s11, s11, s13
	s_lshl_b32 s10, s10, 14
	v_and_b32_e32 v3, 56, v2
	s_add_u32 s10, s1, s10
	v_lshl_or_b32 v2, v0, 11, v3
	s_addc_u32 s11, s11, 0
	s_lshl_b32 s1, s6, 10
	v_lshl_or_b32 v4, v0, 6, v3
	v_ashrrev_i32_e32 v3, 31, v2
	s_add_i32 s19, s1, 0
	v_lshl_add_u64 v[204:205], v[2:3], 1, s[20:21]
	s_mov_b32 m0, s19
	v_ashrrev_i32_e32 v5, 31, v4
	v_lshl_add_u64 v[2:3], v[204:205], 0, s[72:73]
	global_load_lds_dwordx4 v[204:205], off
	s_add_i32 m0, s19, 0x2000
	v_lshl_add_u64 v[206:207], v[4:5], 1, s[10:11]
	global_load_lds_dwordx4 v[2:3], off
	s_add_i32 m0, s19, 0x4000
	s_mov_b64 s[22:23], 0x40000
	v_lshl_add_u64 v[4:5], v[206:207], 0, s[96:97]
	global_load_lds_dwordx4 v[206:207], off
	s_add_i32 m0, s19, 0x6000
	v_lshl_add_u64 v[6:7], v[204:205], 0, s[22:23]
	s_mov_b64 s[20:21], 0x40080
	global_load_lds_dwordx4 v[4:5], off
	s_add_i32 m0, s19, 0x8000
	v_lshl_add_u64 v[8:9], v[204:205], 0, s[20:21]
	global_load_lds_dwordx4 v[6:7], off
	s_add_i32 m0, s19, 0xa000
	v_lshl_add_u64 v[10:11], v[206:207], 0, s[22:23]
	s_mov_b64 s[10:11], 0x42000
	global_load_lds_dwordx4 v[8:9], off
	s_add_i32 m0, s19, 0xc000
	v_lshl_add_u64 v[12:13], v[206:207], 0, s[10:11]
	global_load_lds_dwordx4 v[10:11], off
	s_add_i32 m0, s19, 0xe000
	v_and_b32_e32 v203, 63, v16
	global_load_lds_dwordx4 v[12:13], off
	v_and_b32_e32 v18, 19, v16
	v_lshlrev_b32_e32 v19, 1, v16
	v_lshrrev_b32_e32 v16, 1, v16
	v_and_b32_e32 v19, 8, v19
	v_and_b32_e32 v20, 4, v16
	v_or3_b32 v18, v20, v18, v19
	s_lshl_b32 s1, s15, 13
	v_lshl_or_b32 v217, v18, 7, s1
	v_lshrrev_b32_e32 v18, 1, v18
	v_bitop3_b32 v16, v214, v16, 7 bitop3:0x78
	v_mov_b32_e32 v14, v1
	v_mov_b32_e32 v15, v1
	v_bitop3_b32 v18, v18, v214, 7 bitop3:0x6c
	v_lshlrev_b32_e32 v216, 7, v17
	v_lshlrev_b32_e32 v215, 4, v16
	v_lshlrev_b32_e32 v202, 3, v214
	v_mov_b32_e32 v0, v1
	v_mov_b32_e32 v2, v1
	v_mov_b32_e32 v3, v1
	v_mov_b32_e32 v4, v1
	v_mov_b32_e32 v5, v1
	v_mov_b32_e32 v6, v1
	v_mov_b32_e32 v7, v1
	v_mov_b32_e32 v8, v1
	v_mov_b32_e32 v9, v1
	v_mov_b32_e32 v10, v1
	v_mov_b32_e32 v11, v1
	v_mov_b32_e32 v12, v1
	v_mov_b32_e32 v13, v1
	v_mov_b64_e32 v[80:81], v[14:15]
	v_lshlrev_b32_e32 v218, 4, v18
	v_or_b32_e32 v16, v216, v215
	s_movk_i32 s1, 0x60
	s_lshl_b32 s0, s0, 7
	v_mov_b64_e32 v[64:65], v[14:15]
	v_mov_b64_e32 v[48:49], v[14:15]
	v_mov_b64_e32 v[32:33], v[14:15]
	v_mov_b64_e32 v[78:79], v[12:13]
	v_mov_b64_e32 v[76:77], v[10:11]
	v_mov_b64_e32 v[74:75], v[8:9]
	v_mov_b64_e32 v[72:73], v[6:7]
	v_mov_b64_e32 v[70:71], v[4:5]
	v_mov_b64_e32 v[68:69], v[2:3]
	v_mov_b64_e32 v[66:67], v[0:1]
	v_bitop3_b32 v220, v16, 32, v210 bitop3:0x36
	v_bitop3_b32 v221, v16, 64, v210 bitop3:0x36
	v_bitop3_b32 v222, v16, s1, v210 bitop3:0x36
	v_sub_u32_e32 v226, v17, v202
	s_sub_i32 s0, s7, s0
	v_mov_b32_e32 v227, 0
	v_mov_b64_e32 v[62:63], v[12:13]
	v_mov_b64_e32 v[60:61], v[10:11]
	v_mov_b64_e32 v[58:59], v[8:9]
	v_mov_b64_e32 v[56:57], v[6:7]
	v_mov_b64_e32 v[54:55], v[4:5]
	v_mov_b64_e32 v[52:53], v[2:3]
	v_mov_b64_e32 v[50:51], v[0:1]
	v_mov_b64_e32 v[46:47], v[12:13]
	v_mov_b64_e32 v[44:45], v[10:11]
	v_mov_b64_e32 v[42:43], v[8:9]
	v_mov_b64_e32 v[40:41], v[6:7]
	v_mov_b64_e32 v[38:39], v[4:5]
	v_mov_b64_e32 v[36:37], v[2:3]
	v_mov_b64_e32 v[34:35], v[0:1]
	v_mov_b64_e32 v[30:31], v[12:13]
	v_mov_b64_e32 v[28:29], v[10:11]
	v_mov_b64_e32 v[26:27], v[8:9]
	v_mov_b64_e32 v[24:25], v[6:7]
	v_mov_b64_e32 v[22:23], v[4:5]
	v_mov_b64_e32 v[20:21], v[2:3]
	v_mov_b64_e32 v[18:19], v[0:1]
	v_mov_b64_e32 v[16:17], v[14:15]
	v_mov_b64_e32 v[194:195], 0xaff
	v_mov_b64_e32 v[198:199], 0x200
	s_mov_b32 s9, 3
	s_add_i32 s22, s18, 2
	s_mov_b32 s23, 0
	v_add_u32_e32 v219, 0, v217
	s_or_b32 s27, s18, 1
	v_xor_b32_e32 v223, 32, v218
	v_xor_b32_e32 v224, 64, v218
	v_xor_b32_e32 v225, 0x60, v218
	s_add_i32 s28, s0, 0x1f01
	s_mov_b32 s29, 0x18000
	v_mov_b64_e32 v[14:15], v[12:13]
	v_mov_b64_e32 v[12:13], v[10:11]
	v_mov_b64_e32 v[10:11], v[8:9]
	v_mov_b64_e32 v[8:9], v[6:7]
	v_mov_b64_e32 v[6:7], v[4:5]
	v_mov_b64_e32 v[4:5], v[2:3]
	v_mov_b64_e32 v[2:3], v[0:1]
	v_mov_b32_e32 v228, 0
	s_mov_b32 s30, 0
	v_mov_b32_e32 v98, 0
	v_mov_b32_e32 v99, v227
	v_mov_b32_e32 v100, v227
	v_mov_b32_e32 v101, v227
	v_mov_b32_e32 v102, v227
	v_mov_b32_e32 v103, v227
	v_mov_b32_e32 v104, v227
	v_mov_b32_e32 v105, v227
	v_mov_b32_e32 v106, v227
	v_mov_b32_e32 v107, v227
	v_mov_b32_e32 v108, v227
	v_mov_b32_e32 v109, v227
	v_mov_b32_e32 v110, v227
	v_mov_b32_e32 v111, v227
	v_mov_b32_e32 v112, v227
	v_mov_b32_e32 v113, v227
	v_mov_b32_e32 v82, 0
	v_mov_b32_e32 v83, v227
	v_mov_b32_e32 v84, v227
	v_mov_b32_e32 v85, v227
	v_mov_b32_e32 v86, v227
	v_mov_b32_e32 v87, v227
	v_mov_b32_e32 v88, v227
	v_mov_b32_e32 v89, v227
	v_mov_b32_e32 v90, v227
	v_mov_b32_e32 v91, v227
	v_mov_b32_e32 v92, v227
	v_mov_b32_e32 v93, v227
	v_mov_b32_e32 v94, v227
	v_mov_b32_e32 v95, v227
	v_mov_b32_e32 v96, v227
	v_mov_b32_e32 v97, v227
	s_waitcnt vmcnt(0)
	v_readfirstlane_b32 s101, v208
	s_cmpk_lt_u32 s101, 0x100
	s_cbranch_scc1 .Lda_noprio
	s_setprio 1
.Lda_noprio:
	s_branch .LBB0_263
.LBB0_262:
	s_add_i32 s29, s29, 0x10000
	s_add_i32 s9, s9, 2
	s_addk_i32 s28, 0xff80
	s_add_i32 s23, s23, 0x10000
	s_add_i32 s30, s30, 2
	s_cmp_ge_u32 s31, s18
	s_cbranch_scc1 .LBB0_283

.LBB0_283:
	s_setprio 0
	v_add_f32_e32 v0, 0, v98
	v_add_f32_e32 v0, v99, v0
	v_add_f32_e32 v0, v100, v0
	v_add_f32_e32 v0, v101, v0
	v_add_f32_e32 v0, v102, v0
	v_add_f32_e32 v0, v103, v0
	v_add_f32_e32 v0, v104, v0
	v_add_f32_e32 v0, v105, v0
	v_add_f32_e32 v0, v106, v0
	v_add_f32_e32 v0, v107, v0
	v_add_f32_e32 v0, v108, v0
	v_add_f32_e32 v0, v109, v0
	v_add_f32_e32 v0, v110, v0
	v_add_f32_e32 v0, v111, v0
	v_add_f32_e32 v0, v112, v0
	v_add_f32_e32 v0, v113, v0
	v_add_f32_e32 v0, v0, v82
	s_lshl_b32 s0, s8, 16
	v_add_f32_e32 v0, v83, v0
	s_and_b32 s0, s0, 0x10000
	v_add_f32_e32 v0, v84, v0
	s_add_i32 s0, s0, 0
	v_add_f32_e32 v0, v85, v0
	v_cvt_pk_bf16_f32 v74, v98, v99
	v_cvt_pk_bf16_f32 v75, v100, v101
	v_cvt_pk_bf16_f32 v76, v102, v103
	v_cvt_pk_bf16_f32 v77, v104, v105
	v_cvt_pk_bf16_f32 v70, v82, v83
	v_cvt_pk_bf16_f32 v71, v84, v85
	v_cvt_pk_bf16_f32 v72, v86, v87
	v_add_f32_e32 v0, v86, v0
	v_add_u32_e32 v86, s0, v216
	v_add_f32_e32 v0, v87, v0
	v_add_u32_e32 v87, v86, v215
	v_cvt_pk_bf16_f32 v73, v88, v89
	v_cvt_pk_bf16_f32 v78, v106, v107
	v_cvt_pk_bf16_f32 v79, v108, v109
	v_cvt_pk_bf16_f32 v80, v110, v111
	v_cvt_pk_bf16_f32 v81, v112, v113
	v_cvt_pk_bf16_f32 v66, v90, v91
	v_cvt_pk_bf16_f32 v67, v92, v93
	v_cvt_pk_bf16_f32 v68, v94, v95
	v_cvt_pk_bf16_f32 v69, v96, v97
	ds_read_b128 v[82:85], v87 offset:49152
	s_waitcnt lgkmcnt(0)
	v_mfma_f32_32x32x16_bf16 v[50:65], v[82:85], v[74:77], v[50:65]
	ds_read_b128 v[82:85], v87 offset:53248
	s_movk_i32 s0, 0x60
	v_add_f32_e32 v0, v88, v0
	v_add_f32_e32 v0, v89, v0
	v_add_f32_e32 v0, v90, v0
	v_add_f32_e32 v0, v91, v0
	v_add_f32_e32 v0, v92, v0
	s_waitcnt lgkmcnt(0)
	v_mfma_f32_32x32x16_bf16 v[34:49], v[82:85], v[74:77], v[34:49]
	ds_read_b128 v[82:85], v87 offset:57344
	v_add_f32_e32 v0, v93, v0
	v_add_f32_e32 v0, v94, v0
	v_add_f32_e32 v0, v95, v0
	v_add_f32_e32 v0, v96, v0
	v_add_f32_e32 v0, v97, v0
	v_add_f32_e32 v0, v0, v228
	s_waitcnt lgkmcnt(0)
	v_mfma_f32_32x32x16_bf16 v[18:33], v[82:85], v[74:77], v[18:33]
	ds_read_b128 v[82:85], v87 offset:61440
	s_cmp_eq_u32 s15, 0
	v_mov_b64_e32 v[236:237], v[198:199]
	s_waitcnt lgkmcnt(0)
	v_mfma_f32_32x32x16_bf16 v[2:17], v[82:85], v[74:77], v[2:17]
	v_xad_u32 v82, v215, 32, v86
	ds_read_b128 v[74:77], v82 offset:49152
	s_waitcnt lgkmcnt(0)
	v_mfma_f32_32x32x16_bf16 v[50:65], v[74:77], v[78:81], v[50:65]
	ds_read_b128 v[74:77], v82 offset:53248
	s_waitcnt lgkmcnt(0)
	v_mfma_f32_32x32x16_bf16 v[34:49], v[74:77], v[78:81], v[34:49]
	ds_read_b128 v[74:77], v82 offset:57344
	s_waitcnt lgkmcnt(0)
	v_mfma_f32_32x32x16_bf16 v[18:33], v[74:77], v[78:81], v[18:33]
	ds_read_b128 v[74:77], v82 offset:61440
	s_waitcnt lgkmcnt(0)
	v_mfma_f32_32x32x16_bf16 v[2:17], v[74:77], v[78:81], v[2:17]
	v_xad_u32 v78, v215, 64, v86
	ds_read_b128 v[74:77], v78 offset:49152
	s_waitcnt lgkmcnt(0)
	v_mfma_f32_32x32x16_bf16 v[50:65], v[74:77], v[70:73], v[50:65]
	ds_read_b128 v[74:77], v78 offset:53248
	s_waitcnt lgkmcnt(0)
	v_mfma_f32_32x32x16_bf16 v[34:49], v[74:77], v[70:73], v[34:49]
	ds_read_b128 v[74:77], v78 offset:57344
	s_waitcnt lgkmcnt(0)
	v_mfma_f32_32x32x16_bf16 v[18:33], v[74:77], v[70:73], v[18:33]
	ds_read_b128 v[74:77], v78 offset:61440
	s_waitcnt lgkmcnt(0)
	v_mfma_f32_32x32x16_bf16 v[2:17], v[74:77], v[70:73], v[2:17]
	v_xad_u32 v74, v215, s0, v86
	ds_read_b128 v[70:73], v74 offset:49152
	s_waitcnt lgkmcnt(0)
	v_mfma_f32_32x32x16_bf16 v[50:65], v[70:73], v[66:69], v[50:65]
	ds_read_b128 v[70:73], v74 offset:53248
	s_waitcnt lgkmcnt(0)
	v_mfma_f32_32x32x16_bf16 v[34:49], v[70:73], v[66:69], v[34:49]
	ds_read_b128 v[70:73], v74 offset:57344
	s_waitcnt lgkmcnt(0)
	v_mfma_f32_32x32x16_bf16 v[18:33], v[70:73], v[66:69], v[18:33]
	ds_read_b128 v[70:73], v74 offset:61440
	s_waitcnt vmcnt(0)
	s_waitcnt vmcnt(0) lgkmcnt(0)
	s_barrier
	v_mfma_f32_32x32x16_bf16 v[2:17], v[70:73], v[66:69], v[2:17]
	v_mov_b32_e32 v66, v0
	v_mov_b32_e32 v67, v0
	s_nop 1
	v_permlane32_swap_b32_e32 v66, v67
	v_cndmask_b32_e64 v66, v66, v67, s[38:39]
	v_add_f32_e32 v0, v0, v66
	v_div_scale_f32 v66, s[0:1], v0, v0, 1.0
	v_rcp_f32_e32 v67, v66
	s_cselect_b64 s[0:1], -1, 0
	s_cmp_lg_u32 s15, 0
	v_fma_f32 v68, -v66, v67, 1.0
	v_fmac_f32_e32 v67, v68, v67
	v_div_scale_f32 v68, vcc, 1.0, v0, 1.0
	v_mul_f32_e32 v69, v68, v67
	v_fma_f32 v70, -v66, v69, v68
	v_fmac_f32_e32 v69, v70, v67
	v_fma_f32 v66, -v66, v69, v68
	v_div_fmas_f32 v66, v66, v67, v69
	v_div_fixup_f32 v66, v66, v0, 1.0
	s_cbranch_scc0 .LBB0_285
	s_lshl_b32 s6, s14, 14
	s_add_i32 s6, s6, 0
	v_mul_f32_e32 v0, v50, v66
	v_lshl_add_u32 v67, v203, 2, s6
	v_mul_f32_e32 v68, v51, v66
	ds_write2st64_b32 v67, v0, v68 offset1:1
	v_mul_f32_e32 v0, v52, v66
	v_mul_f32_e32 v68, v53, v66
	ds_write2st64_b32 v67, v0, v68 offset0:2 offset1:3
	v_mul_f32_e32 v0, v54, v66
	v_mul_f32_e32 v68, v55, v66
	ds_write2st64_b32 v67, v0, v68 offset0:4 offset1:5
	v_mul_f32_e32 v0, v56, v66
	v_mul_f32_e32 v68, v57, v66
	ds_write2st64_b32 v67, v0, v68 offset0:6 offset1:7
	v_mul_f32_e32 v0, v58, v66
	v_mul_f32_e32 v68, v59, v66
	ds_write2st64_b32 v67, v0, v68 offset0:8 offset1:9
	v_mul_f32_e32 v0, v60, v66
	v_mul_f32_e32 v68, v61, v66
	ds_write2st64_b32 v67, v0, v68 offset0:10 offset1:11
	v_mul_f32_e32 v0, v62, v66
	v_mul_f32_e32 v68, v63, v66
	ds_write2st64_b32 v67, v0, v68 offset0:12 offset1:13
	v_mul_f32_e32 v0, v64, v66
	v_mul_f32_e32 v68, v65, v66
	ds_write2st64_b32 v67, v0, v68 offset0:14 offset1:15
	v_mul_f32_e32 v0, v34, v66
	v_mul_f32_e32 v68, v35, v66
	ds_write2st64_b32 v67, v0, v68 offset0:16 offset1:17
	v_mul_f32_e32 v0, v36, v66
	v_mul_f32_e32 v68, v37, v66
	ds_write2st64_b32 v67, v0, v68 offset0:18 offset1:19
	v_mul_f32_e32 v0, v38, v66
	v_mul_f32_e32 v68, v39, v66
	ds_write2st64_b32 v67, v0, v68 offset0:20 offset1:21
	v_mul_f32_e32 v0, v40, v66
	v_mul_f32_e32 v68, v41, v66
	ds_write2st64_b32 v67, v0, v68 offset0:22 offset1:23
	v_mul_f32_e32 v0, v42, v66
	v_mul_f32_e32 v68, v43, v66
	ds_write2st64_b32 v67, v0, v68 offset0:24 offset1:25
	v_mul_f32_e32 v0, v44, v66
	v_mul_f32_e32 v68, v45, v66
	ds_write2st64_b32 v67, v0, v68 offset0:26 offset1:27
	v_mul_f32_e32 v0, v46, v66
	v_mul_f32_e32 v68, v47, v66
	ds_write2st64_b32 v67, v0, v68 offset0:28 offset1:29
	v_mul_f32_e32 v0, v48, v66
	v_mul_f32_e32 v68, v49, v66
	ds_write2st64_b32 v67, v0, v68 offset0:30 offset1:31
	v_mul_f32_e32 v0, v18, v66
	v_mul_f32_e32 v68, v19, v66
	ds_write2st64_b32 v67, v0, v68 offset0:32 offset1:33
	v_mul_f32_e32 v0, v20, v66
	v_mul_f32_e32 v68, v21, v66
	ds_write2st64_b32 v67, v0, v68 offset0:34 offset1:35
	v_mul_f32_e32 v0, v22, v66
	v_mul_f32_e32 v68, v23, v66
	ds_write2st64_b32 v67, v0, v68 offset0:36 offset1:37
	v_mul_f32_e32 v0, v24, v66
	v_mul_f32_e32 v68, v25, v66
	ds_write2st64_b32 v67, v0, v68 offset0:38 offset1:39
	v_mul_f32_e32 v0, v26, v66
	v_mul_f32_e32 v68, v27, v66
	ds_write2st64_b32 v67, v0, v68 offset0:40 offset1:41
	v_mul_f32_e32 v0, v28, v66
	v_mul_f32_e32 v68, v29, v66
	ds_write2st64_b32 v67, v0, v68 offset0:42 offset1:43
	v_mul_f32_e32 v0, v30, v66
	v_mul_f32_e32 v68, v31, v66
	ds_write2st64_b32 v67, v0, v68 offset0:44 offset1:45
	v_mul_f32_e32 v0, v32, v66
	v_mul_f32_e32 v68, v33, v66
	ds_write2st64_b32 v67, v0, v68 offset0:46 offset1:47
	v_mul_f32_e32 v0, v2, v66
	v_mul_f32_e32 v68, v3, v66
	ds_write2st64_b32 v67, v0, v68 offset0:48 offset1:49
	v_mul_f32_e32 v0, v4, v66
	v_mul_f32_e32 v68, v5, v66
	ds_write2st64_b32 v67, v0, v68 offset0:50 offset1:51
	v_mul_f32_e32 v0, v6, v66
	v_mul_f32_e32 v68, v7, v66
	ds_write2st64_b32 v67, v0, v68 offset0:52 offset1:53
	v_mul_f32_e32 v0, v8, v66
	v_mul_f32_e32 v68, v9, v66
	ds_write2st64_b32 v67, v0, v68 offset0:54 offset1:55
	v_mul_f32_e32 v0, v10, v66
	v_mul_f32_e32 v68, v11, v66
	ds_write2st64_b32 v67, v0, v68 offset0:56 offset1:57
	v_mul_f32_e32 v0, v12, v66
	v_mul_f32_e32 v68, v13, v66
	ds_write2st64_b32 v67, v0, v68 offset0:58 offset1:59
	v_mul_f32_e32 v0, v14, v66
	v_mul_f32_e32 v68, v15, v66
	ds_write2st64_b32 v67, v0, v68 offset0:60 offset1:61
	v_mul_f32_e32 v0, v16, v66
	v_mul_f32_e32 v68, v17, v66
	ds_write2st64_b32 v67, v0, v68 offset0:62 offset1:63
